# K-loop scalar diet: folded constant adds, dropped s47/s78 temporaries, ds_read or address arithmetic as the M0 wait state instead of s_nop (61 to 40 scalar ops per iteration)
# baseline (speedup 1.0000x reference)
; #define PG8_STAGE(bufoff, gbase, voff) do { _Pragma("unroll") for (int _i = 0; _i < 2; ++_i) \
;         __builtin_amdgcn_global_load_lds((const unsigned*)((const char*)(gbase) + (voff)[_i]), (LAS unsigned*)(lds + (bufoff) + ldsw + _i * 8192), 16, 0, 0); } while (0)
; #define PG8_LDA(dst, b, h) do { _Pragma("unroll") for (int m = 0; m < 4; ++m) _Pragma("unroll") for (int k = 0; k < 2; ++k) dst[m][k] = *(const LAS bf16x8*)(lds + PG8_SA(b, h) + aoff + m * 2048 + k * 1024); } while (0)
; #define PG8_LDB(dst, b, h) do { _Pragma("unroll") for (int n = 0; n < 2; ++n) _Pragma("unroll") for (int k = 0; k < 2; ++k) dst[n][k] = *(const LAS bf16x8*)(lds + PG8_SB(b, h) + boff + n * 2048 + k * 1024); } while (0)
; #define PG8_WAIT_L(n) asm volatile("s_waitcnt lgkmcnt(" #n ")" ::: "memory")
; #define PG8_BAR __builtin_amdgcn_s_barrier()
; #define PG8_SCHED __builtin_amdgcn_sched_barrier(0)
; template <class Epi>
; __device__ __forceinline__ void gemm_phase(LAS unsigned char* lds, const Gemm g, const StaticOrder& S, const Epi& E) {
;     ...
;     for (;;) {
;         const bool has_next = S.next(ui + 1, nxt);
;         const char* nA = has_next ? (const char*)g.A + (size_t)nxt.pm * tstep : cA; const char* nB = has_next ? (const char*)g.Bt + (size_t)nxt.pn * tstep : cB;
;         int t = 0;
; #pragma unroll 1
;         for (int seg = 0; seg < 3; ++seg) {
;         const int tend = (E.mode == 1) ? (seg == 0 ? 12 : (seg == 1 ? 16 : nt)) : (seg == 0 ? nt : 0);
; #pragma unroll 1
;         for (; t < tend; t += 2) {
;             const bool last = (t == nt - 2);
;             const char* a1 = cA + (size_t)(t + 1) * kstep;
;             const char* a2 = last ? nA : cA + (size_t)(t + 2) * kstep; const char* b2 = last ? nB : cB + (size_t)(t + 2) * kstep;
;             const char* a3 = a2 + kstep; const char* b3 = b2 + kstep;
;             PG8_LDB(B0, 0, 0); PG8_SCHED; PG8_LDA(At, 0, 0); PG8_STAGE(PG8_SA(1, 1), a1 + hstep, voffA);
;             PG8_WAIT_L(8); PG8_BAR; PG8_WAIT_L(0); PG8_MMA(0, 0, At, B0); PG8_BAR; PG8_SCHED;
;             PG8_LDB(B1, 0, 1); PG8_STAGE(PG8_SB(0, 0), b2, voffB);
;             PG8_BAR; PG8_WAIT_L(0); PG8_MMA(0, 1, At, B1); PG8_BAR;
;             PG8_LDA(At, 0, 1); PG8_STAGE(PG8_SA(0, 0), a2, voffA);
;             PG8_BAR; PG8_WAIT_L(0); PG8_MMA(1, 0, At, B0); PG8_BAR; PG8_SCHED;
.LBB0_204:
	s_cmp_lg_u32 s56, 1
	s_cselect_b32 s3, s7, 16
	s_cmp_eq_u32 s56, 0
	s_cselect_b32 s57, s7, 0
	s_cselect_b32 s3, 12, s3
	s_and_b64 s[46:47], s[72:73], exec
	s_cselect_b32 s57, s3, s57
	s_cmp_ge_i32 s2, s57
	s_cbranch_scc1 .LBB0_208
	s_ashr_i32 s3, s2, 31
	s_lshl_b64 s[46:47], s[2:3], 7
	s_add_u32 s3, s94, s46
	s_addc_u32 vcc_lo, s95, s47
	s_add_u32 vcc_hi, s50, s46
	s_addc_u32 s46, s51, s47
	v_add_u32_e32 v234, 0x10000, v195
	v_add_u32_e32 v235, 0x14000, v195
	v_add_u32_e32 v236, 0x18000, v195
	v_add_u32_e32 v237, 0x1c000, v195
	s_add_i32 s78, s13, 0x80
.LBB0_206:
	ds_read_b128 v[132:135], v234
	ds_read_b128 v[136:139], v234 offset:1024
	ds_read_b128 v[140:143], v234 offset:2048
	ds_read_b128 v[144:147], v234 offset:3072
	s_add_i32 s76, s2, 1
	s_cmp_eq_u32 s67, s2
	s_cselect_b32 s75, s43, s46
	s_cselect_b32 s74, s42, vcc_hi
	s_cselect_b32 s93, s63, vcc_lo
	s_cselect_b32 s92, s62, s3
	s_add_i32 s2, s2, 2
	s_lshl_b32 s76, s76, 7
	s_add_u32 s76, s5, s76
	s_addc_u32 s77, s31, 0
	s_add_i32 m0, s11, 0xc000
	ds_read_b128 v[148:151], v200
	ds_read_b128 v[152:155], v200 offset:1024
	ds_read_b128 v[156:159], v200 offset:2048
	ds_read_b128 v[160:163], v200 offset:3072
	ds_read_b128 v[164:167], v200 offset:4096
	ds_read_b128 v[186:189], v200 offset:5120
	ds_read_b128 v[190:193], v200 offset:6144
	global_load_lds_dwordx4 v168, s[76:77]
	s_add_i32 m0, s11, 0xe000
	ds_read_b128 v[202:205], v200 offset:7168
	global_load_lds_dwordx4 v172, s[76:77]
	s_waitcnt lgkmcnt(0)
	s_barrier
	v_mfma_f32_16x16x32_bf16 v[128:131], v[132:135], v[148:151], v[128:131]
	v_mfma_f32_16x16x32_bf16 v[124:127], v[140:143], v[148:151], v[124:127]
	v_mfma_f32_16x16x32_bf16 v[112:115], v[132:135], v[156:159], v[112:115]
	v_mfma_f32_16x16x32_bf16 v[108:111], v[140:143], v[156:159], v[108:111]
	v_mfma_f32_16x16x32_bf16 v[96:99], v[132:135], v[164:167], v[96:99]
	v_mfma_f32_16x16x32_bf16 v[92:95], v[140:143], v[164:167], v[92:95]
	v_mfma_f32_16x16x32_bf16 v[80:83], v[132:135], v[190:193], v[80:83]
	v_mfma_f32_16x16x32_bf16 v[76:79], v[140:143], v[190:193], v[76:79]
	v_mfma_f32_16x16x32_bf16 v[128:131], v[136:139], v[152:155], v[128:131]
	v_mfma_f32_16x16x32_bf16 v[124:127], v[144:147], v[152:155], v[124:127]
	v_mfma_f32_16x16x32_bf16 v[112:115], v[136:139], v[160:163], v[112:115]
	v_mfma_f32_16x16x32_bf16 v[108:111], v[144:147], v[160:163], v[108:111]
	v_mfma_f32_16x16x32_bf16 v[96:99], v[136:139], v[186:189], v[96:99]
	v_mfma_f32_16x16x32_bf16 v[92:95], v[144:147], v[186:189], v[92:95]
	v_mfma_f32_16x16x32_bf16 v[80:83], v[136:139], v[202:205], v[80:83]
	v_mfma_f32_16x16x32_bf16 v[76:79], v[144:147], v[202:205], v[76:79]
	s_barrier
	s_add_i32 m0, s6, 0x10000
	ds_read_b128 v[206:209], v235
	ds_read_b128 v[222:225], v235 offset:1024
	ds_read_b128 v[226:229], v235 offset:2048
	global_load_lds_dwordx4 v170, s[92:93]
	s_add_i32 m0, s6, 0x12000
	ds_read_b128 v[230:233], v235 offset:3072
	global_load_lds_dwordx4 v174, s[92:93]
	s_waitcnt lgkmcnt(0)
	s_barrier
	v_mfma_f32_16x16x32_bf16 v[120:123], v[206:209], v[148:151], v[120:123]
	v_mfma_f32_16x16x32_bf16 v[116:119], v[226:229], v[148:151], v[116:119]
	v_mfma_f32_16x16x32_bf16 v[104:107], v[206:209], v[156:159], v[104:107]
	v_mfma_f32_16x16x32_bf16 v[100:103], v[226:229], v[156:159], v[100:103]
	v_mfma_f32_16x16x32_bf16 v[88:91], v[206:209], v[164:167], v[88:91]
	v_mfma_f32_16x16x32_bf16 v[84:87], v[226:229], v[164:167], v[84:87]
	v_mfma_f32_16x16x32_bf16 v[72:75], v[206:209], v[190:193], v[72:75]
	v_mfma_f32_16x16x32_bf16 v[68:71], v[226:229], v[190:193], v[68:71]
	v_mfma_f32_16x16x32_bf16 v[120:123], v[222:225], v[152:155], v[120:123]
	v_mfma_f32_16x16x32_bf16 v[116:119], v[230:233], v[152:155], v[116:119]
	v_mfma_f32_16x16x32_bf16 v[104:107], v[222:225], v[160:163], v[104:107]
	v_mfma_f32_16x16x32_bf16 v[100:103], v[230:233], v[160:163], v[100:103]
	v_mfma_f32_16x16x32_bf16 v[88:91], v[222:225], v[186:189], v[88:91]
	v_mfma_f32_16x16x32_bf16 v[84:87], v[230:233], v[186:189], v[84:87]
	v_mfma_f32_16x16x32_bf16 v[72:75], v[222:225], v[202:205], v[72:75]
	v_mfma_f32_16x16x32_bf16 v[68:71], v[230:233], v[202:205], v[68:71]
	s_mov_b32 m0, s11
	s_barrier
	ds_read_b128 v[148:151], v200 offset:16384
	ds_read_b128 v[152:155], v200 offset:17408
	ds_read_b128 v[156:159], v200 offset:18432
	ds_read_b128 v[160:163], v200 offset:19456
	ds_read_b128 v[164:167], v200 offset:20480
	ds_read_b128 v[186:189], v200 offset:21504
	ds_read_b128 v[190:193], v200 offset:22528
	global_load_lds_dwordx4 v168, s[74:75]
	s_mov_b32 m0, s70
	ds_read_b128 v[202:205], v200 offset:23552
	global_load_lds_dwordx4 v172, s[74:75]
	s_waitcnt lgkmcnt(0)
	s_barrier
	v_mfma_f32_16x16x32_bf16 v[64:67], v[132:135], v[148:151], v[64:67]
	v_mfma_f32_16x16x32_bf16 v[60:63], v[140:143], v[148:151], v[60:63]
	v_mfma_f32_16x16x32_bf16 v[48:51], v[132:135], v[156:159], v[48:51]
	v_mfma_f32_16x16x32_bf16 v[44:47], v[140:143], v[156:159], v[44:47]
	v_mfma_f32_16x16x32_bf16 v[32:35], v[132:135], v[164:167], v[32:35]
	v_mfma_f32_16x16x32_bf16 v[28:31], v[140:143], v[164:167], v[28:31]
	v_mfma_f32_16x16x32_bf16 v[16:19], v[132:135], v[190:193], v[16:19]
	v_mfma_f32_16x16x32_bf16 v[12:15], v[140:143], v[190:193], v[12:15]
	v_mfma_f32_16x16x32_bf16 v[64:67], v[136:139], v[152:155], v[64:67]
	v_mfma_f32_16x16x32_bf16 v[60:63], v[144:147], v[152:155], v[60:63]
	v_mfma_f32_16x16x32_bf16 v[48:51], v[136:139], v[160:163], v[48:51]
	v_mfma_f32_16x16x32_bf16 v[44:47], v[144:147], v[160:163], v[44:47]
	v_mfma_f32_16x16x32_bf16 v[32:35], v[136:139], v[186:189], v[32:35]
	v_mfma_f32_16x16x32_bf16 v[28:31], v[144:147], v[186:189], v[28:31]
	v_mfma_f32_16x16x32_bf16 v[16:19], v[136:139], v[202:205], v[16:19]
	v_mfma_f32_16x16x32_bf16 v[12:15], v[144:147], v[202:205], v[12:15]
	s_barrier
; #define PG8_STAGE(bufoff, gbase, voff) do { _Pragma("unroll") for (int _i = 0; _i < 2; ++_i) \
;         __builtin_amdgcn_global_load_lds((const unsigned*)((const char*)(gbase) + (voff)[_i]), (LAS unsigned*)(lds + (bufoff) + ldsw + _i * 8192), 16, 0, 0); } while (0)
; #define PG8_LDA(dst, b, h) do { _Pragma("unroll") for (int m = 0; m < 4; ++m) _Pragma("unroll") for (int k = 0; k < 2; ++k) dst[m][k] = *(const LAS bf16x8*)(lds + PG8_SA(b, h) + aoff + m * 2048 + k * 1024); } while (0)
; #define PG8_LDB(dst, b, h) do { _Pragma("unroll") for (int n = 0; n < 2; ++n) _Pragma("unroll") for (int k = 0; k < 2; ++k) dst[n][k] = *(const LAS bf16x8*)(lds + PG8_SB(b, h) + boff + n * 2048 + k * 1024); } while (0)
; #define PG8_MMA(ai, bj, At, Bt) do { __builtin_amdgcn_s_setprio(1); _Pragma("unroll") for (int m = 0; m < 4; ++m) _Pragma("unroll") for (int n = 0; n < 2; ++n) _Pragma("unroll") for (int k = 0; k < 2; ++k) \
;         acc[ai][bj][m][n] = __builtin_amdgcn_mfma_f32_16x16x32_bf16(Bt[n][k], At[m][k], acc[ai][bj][m][n], 0, 0, 0); __builtin_amdgcn_s_setprio(0); } while (0)
; #define PG8_WAIT_V(n) asm volatile("s_waitcnt vmcnt(" #n ")" ::: "memory")
; #define PG8_WAIT_L(n) asm volatile("s_waitcnt lgkmcnt(" #n ")" ::: "memory")
; #define PG8_BAR __builtin_amdgcn_s_barrier()
; #define PG8_SCHED __builtin_amdgcn_sched_barrier(0)
; template <class Epi>
; __device__ __forceinline__ void gemm_phase(LAS unsigned char* lds, const Gemm g, const StaticOrder& S, const Epi& E) {
;     ...
;             PG8_STAGE(PG8_SB(0, 1), b2 + hstep, voffB);
;             PG8_WAIT_V(6); PG8_BAR; PG8_MMA(1, 1, At, B1); PG8_BAR;
;             PG8_LDB(B0, 1, 0); PG8_SCHED; PG8_LDA(At, 1, 0); PG8_STAGE(PG8_SA(0, 1), a2 + hstep, voffA);
;             PG8_WAIT_L(8); PG8_BAR; PG8_WAIT_L(0); PG8_MMA(0, 0, At, B0); PG8_BAR; PG8_SCHED;
;             PG8_LDB(B1, 1, 1); PG8_STAGE(PG8_SB(1, 0), b3, voffB);
;             PG8_BAR; PG8_WAIT_L(0); PG8_MMA(0, 1, At, B1); PG8_BAR;
;             PG8_LDA(At, 1, 1); PG8_STAGE(PG8_SA(1, 0), a3, voffA);
;             PG8_BAR; PG8_WAIT_L(0); PG8_MMA(1, 0, At, B0); PG8_BAR; PG8_SCHED;
;             PG8_STAGE(PG8_SB(1, 1), b3 + hstep, voffB);
	s_add_i32 m0, s6, 0x14000
	s_add_u32 s76, s92, s13
	s_addc_u32 s77, s93, 0
	global_load_lds_dwordx4 v170, s[76:77]
	s_add_i32 m0, s6, 0x16000
	s_add_u32 vcc_hi, vcc_hi, 0x100
	s_addc_u32 s46, s46, 0
	global_load_lds_dwordx4 v174, s[76:77]
	s_waitcnt vmcnt(6)
	s_barrier
	v_mfma_f32_16x16x32_bf16 v[56:59], v[206:209], v[148:151], v[56:59]
	v_mfma_f32_16x16x32_bf16 v[52:55], v[226:229], v[148:151], v[52:55]
	v_mfma_f32_16x16x32_bf16 v[40:43], v[206:209], v[156:159], v[40:43]
	v_mfma_f32_16x16x32_bf16 v[36:39], v[226:229], v[156:159], v[36:39]
	v_mfma_f32_16x16x32_bf16 v[24:27], v[206:209], v[164:167], v[24:27]
	v_mfma_f32_16x16x32_bf16 v[20:23], v[226:229], v[164:167], v[20:23]
	v_mfma_f32_16x16x32_bf16 v[8:11], v[206:209], v[190:193], v[8:11]
	v_mfma_f32_16x16x32_bf16 v[4:7], v[226:229], v[190:193], v[4:7]
	v_mfma_f32_16x16x32_bf16 v[56:59], v[222:225], v[152:155], v[56:59]
	v_mfma_f32_16x16x32_bf16 v[52:55], v[230:233], v[152:155], v[52:55]
	v_mfma_f32_16x16x32_bf16 v[40:43], v[222:225], v[160:163], v[40:43]
	v_mfma_f32_16x16x32_bf16 v[36:39], v[230:233], v[160:163], v[36:39]
	v_mfma_f32_16x16x32_bf16 v[24:27], v[222:225], v[186:189], v[24:27]
	v_mfma_f32_16x16x32_bf16 v[20:23], v[230:233], v[186:189], v[20:23]
	v_mfma_f32_16x16x32_bf16 v[8:11], v[222:225], v[202:205], v[8:11]
	v_mfma_f32_16x16x32_bf16 v[4:7], v[230:233], v[202:205], v[4:7]
	s_barrier
	ds_read_b128 v[132:135], v236
	ds_read_b128 v[136:139], v236 offset:1024
	ds_read_b128 v[140:143], v236 offset:2048
	ds_read_b128 v[144:147], v236 offset:3072
	s_add_u32 s76, s74, s13
	s_addc_u32 s77, s75, 0
	s_mov_b32 m0, s71
	ds_read_b128 v[148:151], v200 offset:32768
	ds_read_b128 v[152:155], v200 offset:33792
	ds_read_b128 v[156:159], v200 offset:34816
	ds_read_b128 v[160:163], v200 offset:35840
	ds_read_b128 v[164:167], v200 offset:36864
	ds_read_b128 v[186:189], v200 offset:37888
	ds_read_b128 v[190:193], v200 offset:38912
	global_load_lds_dwordx4 v168, s[76:77]
	s_mov_b32 m0, s19
	ds_read_b128 v[202:205], v200 offset:39936
	global_load_lds_dwordx4 v172, s[76:77]
	s_waitcnt lgkmcnt(0)
	s_barrier
	v_mfma_f32_16x16x32_bf16 v[128:131], v[132:135], v[148:151], v[128:131]
	v_mfma_f32_16x16x32_bf16 v[124:127], v[140:143], v[148:151], v[124:127]
	v_mfma_f32_16x16x32_bf16 v[112:115], v[132:135], v[156:159], v[112:115]
	v_mfma_f32_16x16x32_bf16 v[108:111], v[140:143], v[156:159], v[108:111]
	v_mfma_f32_16x16x32_bf16 v[96:99], v[132:135], v[164:167], v[96:99]
	v_mfma_f32_16x16x32_bf16 v[92:95], v[140:143], v[164:167], v[92:95]
	v_mfma_f32_16x16x32_bf16 v[80:83], v[132:135], v[190:193], v[80:83]
	v_mfma_f32_16x16x32_bf16 v[76:79], v[140:143], v[190:193], v[76:79]
	v_mfma_f32_16x16x32_bf16 v[128:131], v[136:139], v[152:155], v[128:131]
	v_mfma_f32_16x16x32_bf16 v[124:127], v[144:147], v[152:155], v[124:127]
	v_mfma_f32_16x16x32_bf16 v[112:115], v[136:139], v[160:163], v[112:115]
	v_mfma_f32_16x16x32_bf16 v[108:111], v[144:147], v[160:163], v[108:111]
	v_mfma_f32_16x16x32_bf16 v[96:99], v[136:139], v[186:189], v[96:99]
	v_mfma_f32_16x16x32_bf16 v[92:95], v[144:147], v[186:189], v[92:95]
	v_mfma_f32_16x16x32_bf16 v[80:83], v[136:139], v[202:205], v[80:83]
	v_mfma_f32_16x16x32_bf16 v[76:79], v[144:147], v[202:205], v[76:79]
	s_barrier
	s_add_u32 s76, s92, 0x80
	s_addc_u32 s77, s93, 0
	s_add_i32 m0, s6, 0x18000
	ds_read_b128 v[206:209], v237
	ds_read_b128 v[222:225], v237 offset:1024
	ds_read_b128 v[226:229], v237 offset:2048
	global_load_lds_dwordx4 v170, s[76:77]
	s_add_i32 m0, s6, 0x1a000
	ds_read_b128 v[230:233], v237 offset:3072
	global_load_lds_dwordx4 v174, s[76:77]
	s_waitcnt lgkmcnt(0)
	s_barrier
; #define PG8_STAGE(bufoff, gbase, voff) do { _Pragma("unroll") for (int _i = 0; _i < 2; ++_i) \
;         __builtin_amdgcn_global_load_lds((const unsigned*)((const char*)(gbase) + (voff)[_i]), (LAS unsigned*)(lds + (bufoff) + ldsw + _i * 8192), 16, 0, 0); } while (0)
; #define PG8_LDA(dst, b, h) do { _Pragma("unroll") for (int m = 0; m < 4; ++m) _Pragma("unroll") for (int k = 0; k < 2; ++k) dst[m][k] = *(const LAS bf16x8*)(lds + PG8_SA(b, h) + aoff + m * 2048 + k * 1024); } while (0)
; #define PG8_MMA(ai, bj, At, Bt) do { __builtin_amdgcn_s_setprio(1); _Pragma("unroll") for (int m = 0; m < 4; ++m) _Pragma("unroll") for (int n = 0; n < 2; ++n) _Pragma("unroll") for (int k = 0; k < 2; ++k) \
;         acc[ai][bj][m][n] = __builtin_amdgcn_mfma_f32_16x16x32_bf16(Bt[n][k], At[m][k], acc[ai][bj][m][n], 0, 0, 0); __builtin_amdgcn_s_setprio(0); } while (0)
; #define PG8_WAIT_V(n) asm volatile("s_waitcnt vmcnt(" #n ")" ::: "memory")
; #define PG8_WAIT_L(n) asm volatile("s_waitcnt lgkmcnt(" #n ")" ::: "memory")
; #define PG8_BAR __builtin_amdgcn_s_barrier()
; #define PG8_SCHED __builtin_amdgcn_sched_barrier(0)
; template <class Epi>
; __device__ __forceinline__ void gemm_phase(LAS unsigned char* lds, const Gemm g, const StaticOrder& S, const Epi& E) {
;     ...
;             PG8_BAR; PG8_WAIT_L(0); PG8_MMA(0, 1, At, B1); PG8_BAR;
;             PG8_LDA(At, 1, 1); PG8_STAGE(PG8_SA(1, 0), a3, voffA);
;             PG8_BAR; PG8_WAIT_L(0); PG8_MMA(1, 0, At, B0); PG8_BAR; PG8_SCHED;
;             PG8_STAGE(PG8_SB(1, 1), b3 + hstep, voffB);
;             PG8_WAIT_V(6); PG8_BAR; PG8_MMA(1, 1, At, B1); PG8_BAR;
	v_mfma_f32_16x16x32_bf16 v[120:123], v[206:209], v[148:151], v[120:123]
	v_mfma_f32_16x16x32_bf16 v[116:119], v[226:229], v[148:151], v[116:119]
	v_mfma_f32_16x16x32_bf16 v[104:107], v[206:209], v[156:159], v[104:107]
	v_mfma_f32_16x16x32_bf16 v[100:103], v[226:229], v[156:159], v[100:103]
	v_mfma_f32_16x16x32_bf16 v[88:91], v[206:209], v[164:167], v[88:91]
	v_mfma_f32_16x16x32_bf16 v[84:87], v[226:229], v[164:167], v[84:87]
	v_mfma_f32_16x16x32_bf16 v[72:75], v[206:209], v[190:193], v[72:75]
	v_mfma_f32_16x16x32_bf16 v[68:71], v[226:229], v[190:193], v[68:71]
	v_mfma_f32_16x16x32_bf16 v[120:123], v[222:225], v[152:155], v[120:123]
	v_mfma_f32_16x16x32_bf16 v[116:119], v[230:233], v[152:155], v[116:119]
	v_mfma_f32_16x16x32_bf16 v[104:107], v[222:225], v[160:163], v[104:107]
	v_mfma_f32_16x16x32_bf16 v[100:103], v[230:233], v[160:163], v[100:103]
	v_mfma_f32_16x16x32_bf16 v[88:91], v[222:225], v[186:189], v[88:91]
	v_mfma_f32_16x16x32_bf16 v[84:87], v[230:233], v[186:189], v[84:87]
	v_mfma_f32_16x16x32_bf16 v[72:75], v[222:225], v[202:205], v[72:75]
	v_mfma_f32_16x16x32_bf16 v[68:71], v[230:233], v[202:205], v[68:71]
	s_mov_b32 m0, s33
	s_add_u32 s76, s74, 0x80
	s_addc_u32 s77, s75, 0
	s_barrier
	ds_read_b128 v[148:151], v200 offset:49152
	ds_read_b128 v[152:155], v200 offset:50176
	ds_read_b128 v[156:159], v200 offset:51200
	ds_read_b128 v[160:163], v200 offset:52224
	ds_read_b128 v[164:167], v200 offset:53248
	ds_read_b128 v[186:189], v200 offset:54272
	ds_read_b128 v[190:193], v200 offset:55296
	global_load_lds_dwordx4 v168, s[76:77]
	s_mov_b32 m0, s66
	ds_read_b128 v[202:205], v200 offset:56320
	global_load_lds_dwordx4 v172, s[76:77]
	s_waitcnt lgkmcnt(0)
	s_barrier
	v_mfma_f32_16x16x32_bf16 v[64:67], v[132:135], v[148:151], v[64:67]
	v_mfma_f32_16x16x32_bf16 v[60:63], v[140:143], v[148:151], v[60:63]
	v_mfma_f32_16x16x32_bf16 v[48:51], v[132:135], v[156:159], v[48:51]
	v_mfma_f32_16x16x32_bf16 v[44:47], v[140:143], v[156:159], v[44:47]
	v_mfma_f32_16x16x32_bf16 v[32:35], v[132:135], v[164:167], v[32:35]
	v_mfma_f32_16x16x32_bf16 v[28:31], v[140:143], v[164:167], v[28:31]
	v_mfma_f32_16x16x32_bf16 v[16:19], v[132:135], v[190:193], v[16:19]
	v_mfma_f32_16x16x32_bf16 v[12:15], v[140:143], v[190:193], v[12:15]
	v_mfma_f32_16x16x32_bf16 v[64:67], v[136:139], v[152:155], v[64:67]
	v_mfma_f32_16x16x32_bf16 v[60:63], v[144:147], v[152:155], v[60:63]
	v_mfma_f32_16x16x32_bf16 v[48:51], v[136:139], v[160:163], v[48:51]
	v_mfma_f32_16x16x32_bf16 v[44:47], v[144:147], v[160:163], v[44:47]
	v_mfma_f32_16x16x32_bf16 v[32:35], v[136:139], v[186:189], v[32:35]
	v_mfma_f32_16x16x32_bf16 v[28:31], v[144:147], v[186:189], v[28:31]
	v_mfma_f32_16x16x32_bf16 v[16:19], v[136:139], v[202:205], v[16:19]
	v_mfma_f32_16x16x32_bf16 v[12:15], v[144:147], v[202:205], v[12:15]
	s_barrier
	s_add_i32 m0, s6, 0x1c000
	s_add_u32 s76, s92, s78
	s_addc_u32 s77, s93, 0
	global_load_lds_dwordx4 v170, s[76:77]
	s_add_i32 m0, s6, 0x1e000
	s_add_u32 s3, s3, 0x100
	s_addc_u32 vcc_lo, vcc_lo, 0
	global_load_lds_dwordx4 v174, s[76:77]
	s_waitcnt vmcnt(6)
	s_barrier
	v_mfma_f32_16x16x32_bf16 v[56:59], v[206:209], v[148:151], v[56:59]
	v_mfma_f32_16x16x32_bf16 v[52:55], v[226:229], v[148:151], v[52:55]
	v_mfma_f32_16x16x32_bf16 v[40:43], v[206:209], v[156:159], v[40:43]
	v_mfma_f32_16x16x32_bf16 v[36:39], v[226:229], v[156:159], v[36:39]
	v_mfma_f32_16x16x32_bf16 v[24:27], v[206:209], v[164:167], v[24:27]
	v_mfma_f32_16x16x32_bf16 v[20:23], v[226:229], v[164:167], v[20:23]
	v_mfma_f32_16x16x32_bf16 v[8:11], v[206:209], v[190:193], v[8:11]
	v_mfma_f32_16x16x32_bf16 v[4:7], v[226:229], v[190:193], v[4:7]
	v_mfma_f32_16x16x32_bf16 v[56:59], v[222:225], v[152:155], v[56:59]
	v_mfma_f32_16x16x32_bf16 v[52:55], v[230:233], v[152:155], v[52:55]
	v_mfma_f32_16x16x32_bf16 v[40:43], v[222:225], v[160:163], v[40:43]
	v_mfma_f32_16x16x32_bf16 v[36:39], v[230:233], v[160:163], v[36:39]
	v_mfma_f32_16x16x32_bf16 v[24:27], v[222:225], v[186:189], v[24:27]
	v_mfma_f32_16x16x32_bf16 v[20:23], v[230:233], v[186:189], v[20:23]
	v_mfma_f32_16x16x32_bf16 v[8:11], v[222:225], v[202:205], v[8:11]
	v_mfma_f32_16x16x32_bf16 v[4:7], v[230:233], v[202:205], v[4:7]
	s_cmp_lt_i32 s2, s57
	s_barrier
	s_cbranch_scc1 .LBB0_206
	s_movk_i32 s92, 0x90
	s_mov_b32 s93, 0x3f317217
